# out-proj epilogue: x prefetch + counted vmcnt + DPP row reduction instead of ds_bpermute
# speedup vs baseline: 1.0111x; 1.0105x over previous
; DI void st4(u16* d, float a, float b, float c, float e) { *(uint2*)d = make_uint2(pk(a, b), pk(c, e)); }
; DI void phase_outproj(const KArgs& ka, int l, char* lds) {
;     ...
;       for (int j = 0; j < 16; ++j) {
;         const int row = j * 4 + (ln >> 4);
;         const float4 av = *(const float4*)(wl + row * RS + ch * 16);
;         const size_t go = (size_t)(token0 + row) * 1024 + col0 + ch * 4;
;         float4 xo = *(const float4*)(xin + go);
;         xo.x += av.x; xo.y += av.y; xo.z += av.z; xo.w += av.w;
;         *(float4*)(p.out + go) = xo;
;         if (l < DEPTH - 1) {
;           float ss = xo.x * xo.x + xo.y * xo.y + xo.z * xo.z + xo.w * xo.w;
;           st4(p.xg + go, xo.x * g.x, xo.y * g.y, xo.z * g.z, xo.w * g.w);
;           ss += __shfl_xor(ss, 1, 64); ss += __shfl_xor(ss, 2, 64); ss += __shfl_xor(ss, 4, 64); ss += __shfl_xor(ss, 8, 64);
;           if (ch == 0) atomicAdd(p.sumsq_x + (l + 1) * T + token0 + row, ss);
;         }
.Lop_pfskipA:
	v_add_u32_e32 v74, s27, v78
	v_ashrrev_i32_e32 v75, 31, v74
	s_waitcnt lgkmcnt(0)
	v_lshlrev_b64 v[68:69], 10, v[74:75]
	v_lshl_add_u64 v[76:77], v[68:69], 0, v[164:165]
	v_lshlrev_b64 v[84:85], 2, v[76:77]
	v_lshl_add_u64 v[68:69], s[12:13], 0, v[84:85]
	ds_read_b128 v[80:83], v79
	v_cndmask_b32_e64 v75, 0, 1, s[14:15]
	v_cmp_ne_u32_e64 s[4:5], 1, v75
	v_lshl_add_u64 v[84:85], s[52:53], 0, v[84:85]
	s_andn2_b64 vcc, exec, s[14:15]
	s_waitcnt lgkmcnt(0)
	v_pk_add_f32 v[68:69], v[80:81], v[216:217]
	v_pk_add_f32 v[70:71], v[82:83], v[218:219]
	global_store_dwordx4 v[84:85], v[68:71], off
	s_cbranch_vccnz .LBB0_48
	v_pk_mul_f32 v[80:81], v[68:69], v[68:69]
	v_pk_mul_f32 v[82:83], v[70:71], v[70:71]
	v_add_f32_e32 v75, v80, v81
	v_and_b32_e32 v81, 64, v194
	v_add_f32_e32 v75, v75, v82
	v_xor_b32_e32 v80, 1, v194
	v_add_u32_e32 v82, 64, v81
	v_cmp_lt_i32_e32 vcc, v80, v82
	v_add_f32_e32 v75, v75, v83
	v_pk_mul_f32 v[70:71], v[66:67], v[70:71]
	v_cndmask_b32_e32 v80, v194, v80, vcc
	v_lshlrev_b32_e32 v80, 2, v80
	v_mov_b32_dpp v80, v75 row_ror:1 row_mask:0xf bank_mask:0xf
	v_lshl_add_u64 v[76:77], v[76:77], 1, s[0:1]
	s_waitcnt lgkmcnt(0)
	v_add_f32_e32 v75, v75, v80
	v_xor_b32_e32 v80, 2, v194
	v_cmp_lt_i32_e32 vcc, v80, v82
	s_nop 1
	v_cndmask_b32_e32 v80, v194, v80, vcc
	v_lshlrev_b32_e32 v80, 2, v80
	v_mov_b32_dpp v80, v75 row_ror:2 row_mask:0xf bank_mask:0xf
	s_waitcnt lgkmcnt(0)
	v_add_f32_e32 v75, v75, v80
	v_xor_b32_e32 v80, 4, v194
	v_cmp_lt_i32_e32 vcc, v80, v82
	s_nop 1
	v_cndmask_b32_e32 v80, v194, v80, vcc
	v_lshlrev_b32_e32 v80, 2, v80
	v_mov_b32_dpp v83, v75 row_ror:4 row_mask:0xf bank_mask:0xf
	v_pk_mul_f32 v[80:81], v[64:65], v[68:69]
	v_xor_b32_e32 v69, 8, v194
	v_cmp_lt_i32_e32 vcc, v69, v82
	v_cvt_pk_bf16_f32 v80, v80, v81
	s_waitcnt lgkmcnt(0)
	v_add_f32_e32 v68, v75, v83
	v_cndmask_b32_e32 v69, v194, v69, vcc
	v_lshlrev_b32_e32 v69, 2, v69
	v_mov_b32_dpp v69, v68 row_ror:8 row_mask:0xf bank_mask:0xf
	v_cvt_pk_bf16_f32 v81, v70, v71
	global_store_dwordx2 v[76:77], v[80:81], off
	s_and_saveexec_b64 s[28:29], s[8:9]
	s_cbranch_execz .LBB0_47
	s_waitcnt lgkmcnt(0)
	v_add_f32_e32 v68, v68, v69
	global_atomic_add_f32 v[72:73], v68, off offset:-32

; DI void st4(u16* d, float a, float b, float c, float e) { *(uint2*)d = make_uint2(pk(a, b), pk(c, e)); }
; DI void phase_outproj(const KArgs& ka, int l, char* lds) {
;     ...
;           float ss = xo.x * xo.x + xo.y * xo.y + xo.z * xo.z + xo.w * xo.w;
;           st4(p.xg + go, xo.x * g.x, xo.y * g.y, xo.z * g.z, xo.w * g.w);
;           ss += __shfl_xor(ss, 1, 64); ss += __shfl_xor(ss, 2, 64); ss += __shfl_xor(ss, 4, 64); ss += __shfl_xor(ss, 8, 64);
;           if (ch == 0) atomicAdd(p.sumsq_x + (l + 1) * T + token0 + row, ss);
.LBB0_48:
	s_nop 0
	v_add_u32_e32 v68, 4, v74
	s_waitcnt lgkmcnt(0)
	v_ashrrev_i32_e32 v69, 31, v68
	v_lshlrev_b64 v[68:69], 10, v[68:69]
	v_lshl_add_u64 v[76:77], v[68:69], 0, v[164:165]
	v_lshlrev_b64 v[84:85], 2, v[76:77]
	v_lshl_add_u64 v[68:69], s[12:13], 0, v[84:85]
	ds_read_b128 v[80:83], v79 offset:1088
	v_lshl_add_u64 v[84:85], s[52:53], 0, v[84:85]
	s_and_b64 vcc, exec, s[4:5]
	s_waitcnt lgkmcnt(0)
	v_pk_add_f32 v[68:69], v[80:81], v[220:221]
	v_pk_add_f32 v[70:71], v[82:83], v[222:223]
	global_store_dwordx4 v[84:85], v[68:71], off
	s_cbranch_vccnz .LBB0_52
	v_pk_mul_f32 v[80:81], v[68:69], v[68:69]
	v_pk_mul_f32 v[82:83], v[70:71], v[70:71]
	v_add_f32_e32 v75, v80, v81
	v_and_b32_e32 v81, 64, v194
	v_add_f32_e32 v75, v75, v82
	v_xor_b32_e32 v80, 1, v194
	v_add_u32_e32 v82, 64, v81
	v_cmp_lt_i32_e32 vcc, v80, v82
	v_add_f32_e32 v75, v75, v83
	v_pk_mul_f32 v[70:71], v[66:67], v[70:71]
	v_cndmask_b32_e32 v80, v194, v80, vcc
	v_lshlrev_b32_e32 v80, 2, v80
	v_mov_b32_dpp v80, v75 row_ror:1 row_mask:0xf bank_mask:0xf
	v_lshl_add_u64 v[76:77], v[76:77], 1, s[0:1]
	s_waitcnt lgkmcnt(0)
	v_add_f32_e32 v75, v75, v80
	v_xor_b32_e32 v80, 2, v194
	v_cmp_lt_i32_e32 vcc, v80, v82
	s_nop 1
	v_cndmask_b32_e32 v80, v194, v80, vcc
	v_lshlrev_b32_e32 v80, 2, v80
	v_mov_b32_dpp v80, v75 row_ror:2 row_mask:0xf bank_mask:0xf
	s_waitcnt lgkmcnt(0)
	v_add_f32_e32 v75, v75, v80
	v_xor_b32_e32 v80, 4, v194
	v_cmp_lt_i32_e32 vcc, v80, v82
	s_nop 1
	v_cndmask_b32_e32 v80, v194, v80, vcc
	v_lshlrev_b32_e32 v80, 2, v80
	v_mov_b32_dpp v83, v75 row_ror:4 row_mask:0xf bank_mask:0xf
	v_pk_mul_f32 v[80:81], v[64:65], v[68:69]
	v_xor_b32_e32 v69, 8, v194
	v_cmp_lt_i32_e32 vcc, v69, v82
	v_cvt_pk_bf16_f32 v80, v80, v81
	s_waitcnt lgkmcnt(0)
	v_add_f32_e32 v68, v75, v83
	v_cndmask_b32_e32 v69, v194, v69, vcc
	v_lshlrev_b32_e32 v69, 2, v69
	v_mov_b32_dpp v69, v68 row_ror:8 row_mask:0xf bank_mask:0xf
	v_cvt_pk_bf16_f32 v81, v70, v71
	global_store_dwordx2 v[76:77], v[80:81], off
	s_and_saveexec_b64 s[28:29], s[8:9]
	s_cbranch_execz .LBB0_51
	s_waitcnt lgkmcnt(0)
	v_add_f32_e32 v68, v68, v69
	global_atomic_add_f32 v[72:73], v68, off offset:-16

; DI void st4(u16* d, float a, float b, float c, float e) { *(uint2*)d = make_uint2(pk(a, b), pk(c, e)); }
; DI void phase_outproj(const KArgs& ka, int l, char* lds) {
;     ...
;           float ss = xo.x * xo.x + xo.y * xo.y + xo.z * xo.z + xo.w * xo.w;
;           st4(p.xg + go, xo.x * g.x, xo.y * g.y, xo.z * g.z, xo.w * g.w);
;           ss += __shfl_xor(ss, 1, 64); ss += __shfl_xor(ss, 2, 64); ss += __shfl_xor(ss, 4, 64); ss += __shfl_xor(ss, 8, 64);
;           if (ch == 0) atomicAdd(p.sumsq_x + (l + 1) * T + token0 + row, ss);
.LBB0_52:
	s_nop 0
	v_add_u32_e32 v68, 8, v74
	s_waitcnt lgkmcnt(0)
	v_ashrrev_i32_e32 v69, 31, v68
	v_lshlrev_b64 v[68:69], 10, v[68:69]
	v_lshl_add_u64 v[76:77], v[68:69], 0, v[164:165]
	v_lshlrev_b64 v[84:85], 2, v[76:77]
	v_lshl_add_u64 v[68:69], s[12:13], 0, v[84:85]
	ds_read_b128 v[80:83], v79 offset:2176
	v_lshl_add_u64 v[84:85], s[52:53], 0, v[84:85]
	s_and_b64 vcc, exec, s[4:5]
	s_waitcnt lgkmcnt(0)
	v_pk_add_f32 v[68:69], v[80:81], v[224:225]
	v_pk_add_f32 v[70:71], v[82:83], v[226:227]
	global_store_dwordx4 v[84:85], v[68:71], off
	s_cbranch_vccnz .LBB0_56
	v_pk_mul_f32 v[80:81], v[68:69], v[68:69]
	v_pk_mul_f32 v[82:83], v[70:71], v[70:71]
	v_add_f32_e32 v75, v80, v81
	v_and_b32_e32 v81, 64, v194
	v_add_f32_e32 v75, v75, v82
	v_xor_b32_e32 v80, 1, v194
	v_add_u32_e32 v82, 64, v81
	v_cmp_lt_i32_e32 vcc, v80, v82
	v_add_f32_e32 v75, v75, v83
	v_pk_mul_f32 v[70:71], v[66:67], v[70:71]
	v_cndmask_b32_e32 v80, v194, v80, vcc
	v_lshlrev_b32_e32 v80, 2, v80
	v_mov_b32_dpp v80, v75 row_ror:1 row_mask:0xf bank_mask:0xf
	v_lshl_add_u64 v[76:77], v[76:77], 1, s[0:1]
	s_waitcnt lgkmcnt(0)
	v_add_f32_e32 v75, v75, v80
	v_xor_b32_e32 v80, 2, v194
	v_cmp_lt_i32_e32 vcc, v80, v82
	s_nop 1
	v_cndmask_b32_e32 v80, v194, v80, vcc
	v_lshlrev_b32_e32 v80, 2, v80
	v_mov_b32_dpp v80, v75 row_ror:2 row_mask:0xf bank_mask:0xf
	s_waitcnt lgkmcnt(0)
	v_add_f32_e32 v75, v75, v80
	v_xor_b32_e32 v80, 4, v194
	v_cmp_lt_i32_e32 vcc, v80, v82
	s_nop 1
	v_cndmask_b32_e32 v80, v194, v80, vcc
	v_lshlrev_b32_e32 v80, 2, v80
	v_mov_b32_dpp v83, v75 row_ror:4 row_mask:0xf bank_mask:0xf
	v_pk_mul_f32 v[80:81], v[64:65], v[68:69]
	v_xor_b32_e32 v69, 8, v194
	v_cmp_lt_i32_e32 vcc, v69, v82
	v_cvt_pk_bf16_f32 v80, v80, v81
	s_waitcnt lgkmcnt(0)
	v_add_f32_e32 v68, v75, v83
	v_cndmask_b32_e32 v69, v194, v69, vcc
	v_lshlrev_b32_e32 v69, 2, v69
	v_mov_b32_dpp v69, v68 row_ror:8 row_mask:0xf bank_mask:0xf
	v_cvt_pk_bf16_f32 v81, v70, v71
	global_store_dwordx2 v[76:77], v[80:81], off
	s_and_saveexec_b64 s[28:29], s[8:9]
	s_cbranch_execz .LBB0_55
	s_waitcnt lgkmcnt(0)
	v_add_f32_e32 v68, v68, v69
	global_atomic_add_f32 v[72:73], v68, off

; DI void st4(u16* d, float a, float b, float c, float e) { *(uint2*)d = make_uint2(pk(a, b), pk(c, e)); }
; DI void phase_outproj(const KArgs& ka, int l, char* lds) {
;     ...
;           float ss = xo.x * xo.x + xo.y * xo.y + xo.z * xo.z + xo.w * xo.w;
;           st4(p.xg + go, xo.x * g.x, xo.y * g.y, xo.z * g.z, xo.w * g.w);
;           ss += __shfl_xor(ss, 1, 64); ss += __shfl_xor(ss, 2, 64); ss += __shfl_xor(ss, 4, 64); ss += __shfl_xor(ss, 8, 64);
;           if (ch == 0) atomicAdd(p.sumsq_x + (l + 1) * T + token0 + row, ss);
.LBB0_56:
	s_nop 0
	v_add_u32_e32 v68, 12, v74
	s_waitcnt lgkmcnt(0)
	v_ashrrev_i32_e32 v69, 31, v68
	v_lshlrev_b64 v[68:69], 10, v[68:69]
	v_lshl_add_u64 v[74:75], v[68:69], 0, v[164:165]
	v_lshlrev_b64 v[76:77], 2, v[74:75]
	v_lshl_add_u64 v[68:69], s[12:13], 0, v[76:77]
	ds_read_b128 v[80:83], v79 offset:3264
	v_lshl_add_u64 v[76:77], s[52:53], 0, v[76:77]
	s_and_b64 vcc, exec, s[4:5]
	s_waitcnt lgkmcnt(0)
	v_pk_add_f32 v[68:69], v[80:81], v[228:229]
	v_pk_add_f32 v[70:71], v[82:83], v[230:231]
	global_store_dwordx4 v[76:77], v[68:71], off
	s_cbranch_vccnz .LBB0_43
	v_pk_mul_f32 v[76:77], v[68:69], v[68:69]
	v_pk_mul_f32 v[80:81], v[70:71], v[70:71]
	v_add_f32_e32 v76, v76, v77
	v_add_f32_e32 v76, v76, v80
	v_and_b32_e32 v80, 64, v194
	v_xor_b32_e32 v77, 1, v194
	v_add_u32_e32 v80, 64, v80
	v_cmp_lt_i32_e32 vcc, v77, v80
	v_add_f32_e32 v76, v76, v81
	v_pk_mul_f32 v[70:71], v[66:67], v[70:71]
	v_cndmask_b32_e32 v77, v194, v77, vcc
	v_lshlrev_b32_e32 v77, 2, v77
	v_mov_b32_dpp v77, v76 row_ror:1 row_mask:0xf bank_mask:0xf
	v_lshl_add_u64 v[74:75], v[74:75], 1, s[0:1]
	s_waitcnt lgkmcnt(0)
	v_add_f32_e32 v76, v76, v77
	v_xor_b32_e32 v77, 2, v194
	v_cmp_lt_i32_e32 vcc, v77, v80
	s_nop 1
	v_cndmask_b32_e32 v77, v194, v77, vcc
	v_lshlrev_b32_e32 v77, 2, v77
	v_mov_b32_dpp v77, v76 row_ror:2 row_mask:0xf bank_mask:0xf
	s_waitcnt lgkmcnt(0)
	v_add_f32_e32 v81, v76, v77
	v_xor_b32_e32 v76, 4, v194
	v_cmp_lt_i32_e32 vcc, v76, v80
	s_nop 1
	v_cndmask_b32_e32 v76, v194, v76, vcc
	v_lshlrev_b32_e32 v76, 2, v76
	v_mov_b32_dpp v82, v81 row_ror:4 row_mask:0xf bank_mask:0xf
	v_pk_mul_f32 v[76:77], v[64:65], v[68:69]
	v_xor_b32_e32 v69, 8, v194
	v_cmp_lt_i32_e32 vcc, v69, v80
	v_cvt_pk_bf16_f32 v76, v76, v77
	s_waitcnt lgkmcnt(0)
	v_add_f32_e32 v68, v81, v82
	v_cndmask_b32_e32 v69, v194, v69, vcc
	v_lshlrev_b32_e32 v69, 2, v69
	v_mov_b32_dpp v69, v68 row_ror:8 row_mask:0xf bank_mask:0xf
	v_cvt_pk_bf16_f32 v77, v70, v71
	global_store_dwordx2 v[74:75], v[76:77], off
	s_and_saveexec_b64 s[28:29], s[8:9]
	s_cbranch_execz .LBB0_42
	s_waitcnt lgkmcnt(0)
	v_add_f32_e32 v68, v68, v69
	global_atomic_add_f32 v[72:73], v68, off offset:16
	s_branch .LBB0_42

; DI void st4(u16* d, float a, float b, float c, float e) { *(uint2*)d = make_uint2(pk(a, b), pk(c, e)); }
; DI void phase_outproj(const KArgs& ka, int l, char* lds) {
;     ...
;           float ss = xo.x * xo.x + xo.y * xo.y + xo.z * xo.z + xo.w * xo.w;
;           st4(p.xg + go, xo.x * g.x, xo.y * g.y, xo.z * g.z, xo.w * g.w);
;           ss += __shfl_xor(ss, 1, 64); ss += __shfl_xor(ss, 2, 64); ss += __shfl_xor(ss, 4, 64); ss += __shfl_xor(ss, 8, 64);
;           if (ch == 0) atomicAdd(p.sumsq_x + (l + 1) * T + token0 + row, ss);
.Lop_pfskipB:
	v_add_u32_e32 v12, s27, v16
	v_ashrrev_i32_e32 v13, 31, v12
	v_lshlrev_b64 v[14:15], 10, v[12:13]
	s_waitcnt lgkmcnt(0)
	v_lshl_add_u64 v[4:5], v[14:15], 0, v[8:9]
	v_lshlrev_b64 v[22:23], 2, v[4:5]
	v_lshl_add_u64 v[4:5], s[12:13], 0, v[22:23]
	ds_read_b128 v[18:21], v17
	v_lshl_add_u64 v[22:23], s[52:53], 0, v[22:23]
	s_and_b64 vcc, exec, s[4:5]
	s_waitcnt lgkmcnt(0)
	v_pk_add_f32 v[4:5], v[18:19], v[216:217]
	v_pk_add_f32 v[6:7], v[20:21], v[218:219]
	global_store_dwordx4 v[22:23], v[4:7], off offset:256
	s_cbranch_vccnz .LBB0_70
	v_pk_mul_f32 v[18:19], v[4:5], v[4:5]
	v_pk_mul_f32 v[20:21], v[6:7], v[6:7]
	v_add_f32_e32 v13, v18, v19
	v_and_b32_e32 v19, 64, v194
	v_add_f32_e32 v13, v13, v20
	v_xor_b32_e32 v18, 1, v194
	v_add_u32_e32 v20, 64, v19
	v_cmp_lt_i32_e32 vcc, v18, v20
	v_add_f32_e32 v13, v13, v21
	v_lshl_add_u64 v[14:15], v[14:15], 0, v[164:165]
	v_cndmask_b32_e32 v18, v194, v18, vcc
	v_lshlrev_b32_e32 v18, 2, v18
	v_mov_b32_dpp v18, v13 row_ror:1 row_mask:0xf bank_mask:0xf
	v_pk_mul_f32 v[6:7], v[2:3], v[6:7]
	v_lshl_add_u64 v[14:15], v[14:15], 1, s[0:1]
	s_waitcnt lgkmcnt(0)
	v_add_f32_e32 v13, v13, v18
	v_xor_b32_e32 v18, 2, v194
	v_cmp_lt_i32_e32 vcc, v18, v20
	s_nop 1
	v_cndmask_b32_e32 v18, v194, v18, vcc
	v_lshlrev_b32_e32 v18, 2, v18
	v_mov_b32_dpp v18, v13 row_ror:2 row_mask:0xf bank_mask:0xf
	s_waitcnt lgkmcnt(0)
	v_add_f32_e32 v13, v13, v18
	v_xor_b32_e32 v18, 4, v194
	v_cmp_lt_i32_e32 vcc, v18, v20
	s_nop 1
	v_cndmask_b32_e32 v18, v194, v18, vcc
	v_lshlrev_b32_e32 v18, 2, v18
	v_mov_b32_dpp v21, v13 row_ror:4 row_mask:0xf bank_mask:0xf
	v_pk_mul_f32 v[18:19], v[0:1], v[4:5]
	v_xor_b32_e32 v5, 8, v194
	v_cmp_lt_i32_e32 vcc, v5, v20
	v_cvt_pk_bf16_f32 v18, v18, v19
	s_waitcnt lgkmcnt(0)
	v_add_f32_e32 v4, v13, v21
	v_cndmask_b32_e32 v5, v194, v5, vcc
	v_lshlrev_b32_e32 v5, 2, v5
	v_mov_b32_dpp v5, v4 row_ror:8 row_mask:0xf bank_mask:0xf
	v_cvt_pk_bf16_f32 v19, v6, v7
	global_store_dwordx2 v[14:15], v[18:19], off
	s_and_saveexec_b64 s[8:9], s[6:7]
	s_cbranch_execz .LBB0_69
	s_waitcnt lgkmcnt(0)
	v_add_f32_e32 v4, v4, v5
	global_atomic_add_f32 v[10:11], v4, off offset:-32

; DI void st4(u16* d, float a, float b, float c, float e) { *(uint2*)d = make_uint2(pk(a, b), pk(c, e)); }
; DI void phase_outproj(const KArgs& ka, int l, char* lds) {
;     ...
;           float ss = xo.x * xo.x + xo.y * xo.y + xo.z * xo.z + xo.w * xo.w;
;           st4(p.xg + go, xo.x * g.x, xo.y * g.y, xo.z * g.z, xo.w * g.w);
;           ss += __shfl_xor(ss, 1, 64); ss += __shfl_xor(ss, 2, 64); ss += __shfl_xor(ss, 4, 64); ss += __shfl_xor(ss, 8, 64);
;           if (ch == 0) atomicAdd(p.sumsq_x + (l + 1) * T + token0 + row, ss);
.LBB0_70:
	s_nop 0
	v_add_u32_e32 v4, 4, v12
	s_waitcnt lgkmcnt(0)
	v_ashrrev_i32_e32 v5, 31, v4
	v_lshlrev_b64 v[14:15], 10, v[4:5]
	v_lshl_add_u64 v[4:5], v[14:15], 0, v[8:9]
	v_lshlrev_b64 v[22:23], 2, v[4:5]
	v_lshl_add_u64 v[4:5], s[12:13], 0, v[22:23]
	ds_read_b128 v[18:21], v17 offset:1088
	v_lshl_add_u64 v[22:23], s[52:53], 0, v[22:23]
	s_and_b64 vcc, exec, s[4:5]
	s_waitcnt lgkmcnt(0)
	v_pk_add_f32 v[4:5], v[18:19], v[220:221]
	v_pk_add_f32 v[6:7], v[20:21], v[222:223]
	global_store_dwordx4 v[22:23], v[4:7], off offset:256
	s_cbranch_vccnz .LBB0_74
	v_pk_mul_f32 v[18:19], v[4:5], v[4:5]
	v_pk_mul_f32 v[20:21], v[6:7], v[6:7]
	v_add_f32_e32 v13, v18, v19
	v_and_b32_e32 v19, 64, v194
	v_add_f32_e32 v13, v13, v20
	v_xor_b32_e32 v18, 1, v194
	v_add_u32_e32 v20, 64, v19
	v_cmp_lt_i32_e32 vcc, v18, v20
	v_add_f32_e32 v13, v13, v21
	v_lshl_add_u64 v[14:15], v[14:15], 0, v[164:165]
	v_cndmask_b32_e32 v18, v194, v18, vcc
	v_lshlrev_b32_e32 v18, 2, v18
	v_mov_b32_dpp v18, v13 row_ror:1 row_mask:0xf bank_mask:0xf
	v_pk_mul_f32 v[6:7], v[2:3], v[6:7]
	v_lshl_add_u64 v[14:15], v[14:15], 1, s[0:1]
	s_waitcnt lgkmcnt(0)
	v_add_f32_e32 v13, v13, v18
	v_xor_b32_e32 v18, 2, v194
	v_cmp_lt_i32_e32 vcc, v18, v20
	s_nop 1
	v_cndmask_b32_e32 v18, v194, v18, vcc
	v_lshlrev_b32_e32 v18, 2, v18
	v_mov_b32_dpp v18, v13 row_ror:2 row_mask:0xf bank_mask:0xf
	s_waitcnt lgkmcnt(0)
	v_add_f32_e32 v13, v13, v18
	v_xor_b32_e32 v18, 4, v194
	v_cmp_lt_i32_e32 vcc, v18, v20
	s_nop 1
	v_cndmask_b32_e32 v18, v194, v18, vcc
	v_lshlrev_b32_e32 v18, 2, v18
	v_mov_b32_dpp v21, v13 row_ror:4 row_mask:0xf bank_mask:0xf
	v_pk_mul_f32 v[18:19], v[0:1], v[4:5]
	v_xor_b32_e32 v5, 8, v194
	v_cmp_lt_i32_e32 vcc, v5, v20
	v_cvt_pk_bf16_f32 v18, v18, v19
	s_waitcnt lgkmcnt(0)
	v_add_f32_e32 v4, v13, v21
	v_cndmask_b32_e32 v5, v194, v5, vcc
	v_lshlrev_b32_e32 v5, 2, v5
	v_mov_b32_dpp v5, v4 row_ror:8 row_mask:0xf bank_mask:0xf
	v_cvt_pk_bf16_f32 v19, v6, v7
	global_store_dwordx2 v[14:15], v[18:19], off
	s_and_saveexec_b64 s[8:9], s[6:7]
	s_cbranch_execz .LBB0_73
	s_waitcnt lgkmcnt(0)
	v_add_f32_e32 v4, v4, v5
	global_atomic_add_f32 v[10:11], v4, off offset:-16

; DI void st4(u16* d, float a, float b, float c, float e) { *(uint2*)d = make_uint2(pk(a, b), pk(c, e)); }
; DI void phase_outproj(const KArgs& ka, int l, char* lds) {
;     ...
;           float ss = xo.x * xo.x + xo.y * xo.y + xo.z * xo.z + xo.w * xo.w;
;           st4(p.xg + go, xo.x * g.x, xo.y * g.y, xo.z * g.z, xo.w * g.w);
;           ss += __shfl_xor(ss, 1, 64); ss += __shfl_xor(ss, 2, 64); ss += __shfl_xor(ss, 4, 64); ss += __shfl_xor(ss, 8, 64);
;           if (ch == 0) atomicAdd(p.sumsq_x + (l + 1) * T + token0 + row, ss);
.LBB0_74:
	s_nop 0
	v_add_u32_e32 v4, 8, v12
	s_waitcnt lgkmcnt(0)
	v_ashrrev_i32_e32 v5, 31, v4
	v_lshlrev_b64 v[14:15], 10, v[4:5]
	v_lshl_add_u64 v[4:5], v[14:15], 0, v[8:9]
	v_lshlrev_b64 v[22:23], 2, v[4:5]
	v_lshl_add_u64 v[4:5], s[12:13], 0, v[22:23]
	ds_read_b128 v[18:21], v17 offset:2176
	v_lshl_add_u64 v[22:23], s[52:53], 0, v[22:23]
	s_and_b64 vcc, exec, s[4:5]
	s_waitcnt lgkmcnt(0)
	v_pk_add_f32 v[4:5], v[18:19], v[224:225]
	v_pk_add_f32 v[6:7], v[20:21], v[226:227]
	global_store_dwordx4 v[22:23], v[4:7], off offset:256
	s_cbranch_vccnz .LBB0_78
	v_pk_mul_f32 v[18:19], v[4:5], v[4:5]
	v_pk_mul_f32 v[20:21], v[6:7], v[6:7]
	v_add_f32_e32 v13, v18, v19
	v_and_b32_e32 v19, 64, v194
	v_add_f32_e32 v13, v13, v20
	v_xor_b32_e32 v18, 1, v194
	v_add_u32_e32 v20, 64, v19
	v_cmp_lt_i32_e32 vcc, v18, v20
	v_add_f32_e32 v13, v13, v21
	v_lshl_add_u64 v[14:15], v[14:15], 0, v[164:165]
	v_cndmask_b32_e32 v18, v194, v18, vcc
	v_lshlrev_b32_e32 v18, 2, v18
	v_mov_b32_dpp v18, v13 row_ror:1 row_mask:0xf bank_mask:0xf
	v_pk_mul_f32 v[6:7], v[2:3], v[6:7]
	v_lshl_add_u64 v[14:15], v[14:15], 1, s[0:1]
	s_waitcnt lgkmcnt(0)
	v_add_f32_e32 v13, v13, v18
	v_xor_b32_e32 v18, 2, v194
	v_cmp_lt_i32_e32 vcc, v18, v20
	s_nop 1
	v_cndmask_b32_e32 v18, v194, v18, vcc
	v_lshlrev_b32_e32 v18, 2, v18
	v_mov_b32_dpp v18, v13 row_ror:2 row_mask:0xf bank_mask:0xf
	s_waitcnt lgkmcnt(0)
	v_add_f32_e32 v13, v13, v18
	v_xor_b32_e32 v18, 4, v194
	v_cmp_lt_i32_e32 vcc, v18, v20
	s_nop 1
	v_cndmask_b32_e32 v18, v194, v18, vcc
	v_lshlrev_b32_e32 v18, 2, v18
	v_mov_b32_dpp v21, v13 row_ror:4 row_mask:0xf bank_mask:0xf
	v_pk_mul_f32 v[18:19], v[0:1], v[4:5]
	v_xor_b32_e32 v5, 8, v194
	v_cmp_lt_i32_e32 vcc, v5, v20
	v_cvt_pk_bf16_f32 v18, v18, v19
	s_waitcnt lgkmcnt(0)
	v_add_f32_e32 v4, v13, v21
	v_cndmask_b32_e32 v5, v194, v5, vcc
	v_lshlrev_b32_e32 v5, 2, v5
	v_mov_b32_dpp v5, v4 row_ror:8 row_mask:0xf bank_mask:0xf
	v_cvt_pk_bf16_f32 v19, v6, v7
	global_store_dwordx2 v[14:15], v[18:19], off
	s_and_saveexec_b64 s[8:9], s[6:7]
	s_cbranch_execz .LBB0_77
	s_waitcnt lgkmcnt(0)
	v_add_f32_e32 v4, v4, v5
	global_atomic_add_f32 v[10:11], v4, off

; DI void st4(u16* d, float a, float b, float c, float e) { *(uint2*)d = make_uint2(pk(a, b), pk(c, e)); }
; DI void phase_outproj(const KArgs& ka, int l, char* lds) {
;     ...
;           float ss = xo.x * xo.x + xo.y * xo.y + xo.z * xo.z + xo.w * xo.w;
;           st4(p.xg + go, xo.x * g.x, xo.y * g.y, xo.z * g.z, xo.w * g.w);
;           ss += __shfl_xor(ss, 1, 64); ss += __shfl_xor(ss, 2, 64); ss += __shfl_xor(ss, 4, 64); ss += __shfl_xor(ss, 8, 64);
;           if (ch == 0) atomicAdd(p.sumsq_x + (l + 1) * T + token0 + row, ss);
.LBB0_78:
	s_nop 0
	v_add_u32_e32 v4, 12, v12
	s_waitcnt lgkmcnt(0)
	v_ashrrev_i32_e32 v5, 31, v4
	v_lshlrev_b64 v[12:13], 10, v[4:5]
	v_lshl_add_u64 v[4:5], v[12:13], 0, v[8:9]
	v_lshlrev_b64 v[14:15], 2, v[4:5]
	v_lshl_add_u64 v[4:5], s[12:13], 0, v[14:15]
	ds_read_b128 v[18:21], v17 offset:3264
	v_lshl_add_u64 v[14:15], s[52:53], 0, v[14:15]
	s_and_b64 vcc, exec, s[4:5]
	s_waitcnt lgkmcnt(0)
	v_pk_add_f32 v[4:5], v[18:19], v[228:229]
	v_pk_add_f32 v[6:7], v[20:21], v[230:231]
	global_store_dwordx4 v[14:15], v[4:7], off offset:256
	s_cbranch_vccnz .LBB0_65
	v_pk_mul_f32 v[14:15], v[4:5], v[4:5]
	v_pk_mul_f32 v[18:19], v[6:7], v[6:7]
	v_add_f32_e32 v14, v14, v15
	v_add_f32_e32 v14, v14, v18
	v_and_b32_e32 v18, 64, v194
	v_xor_b32_e32 v15, 1, v194
	v_add_u32_e32 v18, 64, v18
	v_cmp_lt_i32_e32 vcc, v15, v18
	v_add_f32_e32 v14, v14, v19
	v_lshl_add_u64 v[12:13], v[12:13], 0, v[164:165]
	v_cndmask_b32_e32 v15, v194, v15, vcc
	v_lshlrev_b32_e32 v15, 2, v15
	v_mov_b32_dpp v15, v14 row_ror:1 row_mask:0xf bank_mask:0xf
	v_pk_mul_f32 v[6:7], v[2:3], v[6:7]
	v_lshl_add_u64 v[12:13], v[12:13], 1, s[0:1]
	s_waitcnt lgkmcnt(0)
	v_add_f32_e32 v14, v14, v15
	v_xor_b32_e32 v15, 2, v194
	v_cmp_lt_i32_e32 vcc, v15, v18
	s_nop 1
	v_cndmask_b32_e32 v15, v194, v15, vcc
	v_lshlrev_b32_e32 v15, 2, v15
	v_mov_b32_dpp v15, v14 row_ror:2 row_mask:0xf bank_mask:0xf
	s_waitcnt lgkmcnt(0)
	v_add_f32_e32 v19, v14, v15
	v_xor_b32_e32 v14, 4, v194
	v_cmp_lt_i32_e32 vcc, v14, v18
	s_nop 1
	v_cndmask_b32_e32 v14, v194, v14, vcc
	v_lshlrev_b32_e32 v14, 2, v14
	v_mov_b32_dpp v20, v19 row_ror:4 row_mask:0xf bank_mask:0xf
	v_pk_mul_f32 v[14:15], v[0:1], v[4:5]
	v_xor_b32_e32 v5, 8, v194
	v_cmp_lt_i32_e32 vcc, v5, v18
	v_cvt_pk_bf16_f32 v14, v14, v15
	s_waitcnt lgkmcnt(0)
	v_add_f32_e32 v4, v19, v20
	v_cndmask_b32_e32 v5, v194, v5, vcc
	v_lshlrev_b32_e32 v5, 2, v5
	v_mov_b32_dpp v5, v4 row_ror:8 row_mask:0xf bank_mask:0xf
	v_cvt_pk_bf16_f32 v15, v6, v7
	global_store_dwordx2 v[12:13], v[14:15], off
	s_and_saveexec_b64 s[8:9], s[6:7]
	s_cbranch_execz .LBB0_64
	s_waitcnt lgkmcnt(0)
	v_add_f32_e32 v4, v4, v5
	global_atomic_add_f32 v[10:11], v4, off offset:16
	s_branch .LBB0_64
